# hand-scheduled packed-f32 EpiGU epilogue (P5,P11): pipelined partial-sum loads, v_pk_* math, -38% VALU cycles
# baseline (speedup 1.0000x reference)
; __device__ __forceinline__ u32x4v pack8(const f32x4& a, const f32x4& b) { u32x4v w; w.x = cvt_pk_bf16(a[0], a[1]); w.y = cvt_pk_bf16(a[2], a[3]); w.z = cvt_pk_bf16(b[0], b[1]); w.w = cvt_pk_bf16(b[2], b[3]); return w; }
; __device__ __forceinline__ float rstd_from_partials(const float* part, int row) {
;     const f32x4* p = (const f32x4*)(part + (size_t)row * 16); const f32x4 a = p[0], b = p[1], c = p[2], d = p[3];
;     const float s = ((a[0] + a[1]) + (a[2] + a[3])) + ((b[0] + b[1]) + (b[2] + b[3])) + ((c[0] + c[1]) + (c[2] + c[3])) + ((d[0] + d[1]) + (d[2] + d[3]));
;     return __builtin_amdgcn_rsqf(s * (1.0f / 1024.0f) + 1e-6f);
; }
;     __device__ __forceinline__ void operator()(const f32x4 (&acc)[2][2][4][2], const Unit& u, int wr, int wc, int fr, int fq) const {
;         const int row0 = u.pm * BM + wr * 64 + fr, hc0 = u.pn * HALF + wc * 32 + 8 * fq;
; #pragma unroll
;         for (int ai = 0; ai < 2; ++ai)
; #pragma unroll
;             for (int m = 0; m < 4; ++m) { const int r = row0 + ai * HALF + m * 16; const float rs = rstd_from_partials(part, r);
;                 f32x4 o[2];
; #pragma unroll
;                 for (int n = 0; n < 2; ++n) { const f32x4 g = acc[ai][0][m][n] * rs, up = acc[ai][1][m][n] * rs;
; #pragma unroll
;                     for (int e = 0; e < 4; ++e) o[n][e] = g[e] * __builtin_amdgcn_rcpf(1.0f + __builtin_amdgcn_exp2f(-1.44269504089f * g[e])) * up[e]; }
;                 *(u32x4v*)(H + (size_t)r * 2816 + hc0) = pack8(o[0], o[1]); }
;     }
.LBB0_578:
	v_lshl_add_u32 v144, s28, 8, v146
	v_lshlrev_b32_e32 v145, 6, v144
	v_add_u32_e32 v153, 0x2000, v145
	global_load_dwordx4 v[154:157], v145, s[70:71] offset:0
	global_load_dwordx4 v[158:161], v145, s[70:71] offset:16
	global_load_dwordx4 v[162:165], v145, s[70:71] offset:32
	global_load_dwordx4 v[166:169], v145, s[70:71] offset:48
	global_load_dwordx4 v[170:173], v145, s[70:71] offset:1024
	global_load_dwordx4 v[174:177], v145, s[70:71] offset:1040
	global_load_dwordx4 v[178:181], v145, s[70:71] offset:1056
	global_load_dwordx4 v[182:185], v145, s[70:71] offset:1072
	global_load_dwordx4 v[186:189], v145, s[70:71] offset:2048
	global_load_dwordx4 v[190:193], v145, s[70:71] offset:2064
	global_load_dwordx4 v[194:197], v145, s[70:71] offset:2080
	global_load_dwordx4 v[198:201], v145, s[70:71] offset:2096
	global_load_dwordx4 v[202:205], v145, s[70:71] offset:3072
	global_load_dwordx4 v[206:209], v145, s[70:71] offset:3088
	global_load_dwordx4 v[210:213], v145, s[70:71] offset:3104
	global_load_dwordx4 v[214:217], v145, s[70:71] offset:3120
	v_mov_b32_e32 v224, 0xbfb8aa3b
	v_mov_b32_e32 v226, 1.0
	v_mul_u32_u24_e32 v218, s55, v144
	v_lshl_or_b32 v219, s56, 7, v148
	v_lshl_add_u32 v218, v219, 1, v218
	s_waitcnt vmcnt(12)
	v_pk_add_f32 v[154:155], v[154:155], v[156:157]
	v_pk_add_f32 v[158:159], v[158:159], v[160:161]
	v_pk_add_f32 v[162:163], v[162:163], v[164:165]
	v_pk_add_f32 v[166:167], v[166:167], v[168:169]
	v_pk_add_f32 v[154:155], v[154:155], v[158:159]
	v_pk_add_f32 v[162:163], v[162:163], v[166:167]
	v_pk_add_f32 v[154:155], v[154:155], v[162:163]
	v_add_f32_e32 v154, v154, v155
	v_fmamk_f32 v222, v154, 0x3a800000, v152
	v_rsq_f32_e32 v222, v222
	global_load_dwordx4 v[154:157], v153, s[70:71] offset:0
	global_load_dwordx4 v[158:161], v153, s[70:71] offset:16
	global_load_dwordx4 v[162:165], v153, s[70:71] offset:32
	global_load_dwordx4 v[166:169], v153, s[70:71] offset:48
	v_mov_b32_e32 v238, v218
	v_pk_mul_f32 v[116:117], v[116:117], v[222:223] op_sel_hi:[1,0]
	v_pk_mul_f32 v[118:119], v[118:119], v[222:223] op_sel_hi:[1,0]
	v_pk_mul_f32 v[112:113], v[112:113], v[222:223] op_sel_hi:[1,0]
	v_pk_mul_f32 v[114:115], v[114:115], v[222:223] op_sel_hi:[1,0]
	v_pk_mul_f32 v[124:125], v[124:125], v[222:223] op_sel_hi:[1,0]
	v_pk_mul_f32 v[126:127], v[126:127], v[222:223] op_sel_hi:[1,0]
	v_pk_mul_f32 v[120:121], v[120:121], v[222:223] op_sel_hi:[1,0]
	v_pk_mul_f32 v[122:123], v[122:123], v[222:223] op_sel_hi:[1,0]
	v_pk_mul_f32 v[230:231], v[116:117], v[224:225] op_sel_hi:[1,0]
	v_pk_mul_f32 v[232:233], v[118:119], v[224:225] op_sel_hi:[1,0]
	v_pk_mul_f32 v[234:235], v[112:113], v[224:225] op_sel_hi:[1,0]
	v_pk_mul_f32 v[236:237], v[114:115], v[224:225] op_sel_hi:[1,0]
	v_exp_f32_e32 v230, v230
	v_exp_f32_e32 v231, v231
	v_exp_f32_e32 v232, v232
	v_exp_f32_e32 v233, v233
	v_exp_f32_e32 v234, v234
	v_exp_f32_e32 v235, v235
	v_exp_f32_e32 v236, v236
	v_exp_f32_e32 v237, v237
	v_pk_add_f32 v[230:231], v[230:231], v[226:227] op_sel_hi:[1,0]
	v_pk_add_f32 v[232:233], v[232:233], v[226:227] op_sel_hi:[1,0]
	v_pk_add_f32 v[234:235], v[234:235], v[226:227] op_sel_hi:[1,0]
	v_pk_add_f32 v[236:237], v[236:237], v[226:227] op_sel_hi:[1,0]
	v_rcp_f32_e32 v230, v230
	v_rcp_f32_e32 v231, v231
	v_rcp_f32_e32 v232, v232
	v_rcp_f32_e32 v233, v233
	v_rcp_f32_e32 v234, v234
	v_rcp_f32_e32 v235, v235
	v_rcp_f32_e32 v236, v236
	v_rcp_f32_e32 v237, v237
	v_pk_mul_f32 v[116:117], v[116:117], v[230:231]
	v_pk_mul_f32 v[118:119], v[118:119], v[232:233]
	v_pk_mul_f32 v[112:113], v[112:113], v[234:235]
	v_pk_mul_f32 v[114:115], v[114:115], v[236:237]
	v_pk_mul_f32 v[116:117], v[124:125], v[116:117]
	v_pk_mul_f32 v[118:119], v[126:127], v[118:119]
	v_pk_mul_f32 v[112:113], v[120:121], v[112:113]
	v_pk_mul_f32 v[114:115], v[122:123], v[114:115]
	v_cvt_pk_bf16_f32 v124, v116, v117
	v_cvt_pk_bf16_f32 v125, v118, v119
	v_cvt_pk_bf16_f32 v126, v112, v113
	v_cvt_pk_bf16_f32 v127, v114, v115
	global_store_dwordx4 v238, v[124:127], s[40:41]
	s_waitcnt vmcnt(12)
	v_pk_add_f32 v[170:171], v[170:171], v[172:173]
	v_pk_add_f32 v[174:175], v[174:175], v[176:177]
	v_pk_add_f32 v[178:179], v[178:179], v[180:181]
	v_pk_add_f32 v[182:183], v[182:183], v[184:185]
	v_pk_add_f32 v[170:171], v[170:171], v[174:175]
	v_pk_add_f32 v[178:179], v[178:179], v[182:183]
	v_pk_add_f32 v[170:171], v[170:171], v[178:179]
	v_add_f32_e32 v170, v170, v171
	v_fmamk_f32 v222, v170, 0x3a800000, v152
	v_rsq_f32_e32 v222, v222
	global_load_dwordx4 v[170:173], v153, s[70:71] offset:1024
	global_load_dwordx4 v[174:177], v153, s[70:71] offset:1040
	global_load_dwordx4 v[178:181], v153, s[70:71] offset:1056
	global_load_dwordx4 v[182:185], v153, s[70:71] offset:1072
	v_add_u32_e32 v239, 0x16000, v218
	v_pk_mul_f32 v[100:101], v[100:101], v[222:223] op_sel_hi:[1,0]
	v_pk_mul_f32 v[102:103], v[102:103], v[222:223] op_sel_hi:[1,0]
	v_pk_mul_f32 v[96:97], v[96:97], v[222:223] op_sel_hi:[1,0]
	v_pk_mul_f32 v[98:99], v[98:99], v[222:223] op_sel_hi:[1,0]
	v_pk_mul_f32 v[108:109], v[108:109], v[222:223] op_sel_hi:[1,0]
	v_pk_mul_f32 v[110:111], v[110:111], v[222:223] op_sel_hi:[1,0]
	v_pk_mul_f32 v[104:105], v[104:105], v[222:223] op_sel_hi:[1,0]
	v_pk_mul_f32 v[106:107], v[106:107], v[222:223] op_sel_hi:[1,0]
	v_pk_mul_f32 v[230:231], v[100:101], v[224:225] op_sel_hi:[1,0]
	v_pk_mul_f32 v[232:233], v[102:103], v[224:225] op_sel_hi:[1,0]
	v_pk_mul_f32 v[234:235], v[96:97], v[224:225] op_sel_hi:[1,0]
	v_pk_mul_f32 v[236:237], v[98:99], v[224:225] op_sel_hi:[1,0]
	v_exp_f32_e32 v230, v230
	v_exp_f32_e32 v231, v231
	v_exp_f32_e32 v232, v232
	v_exp_f32_e32 v233, v233
	v_exp_f32_e32 v234, v234
	v_exp_f32_e32 v235, v235
	v_exp_f32_e32 v236, v236
	v_exp_f32_e32 v237, v237
	v_pk_add_f32 v[230:231], v[230:231], v[226:227] op_sel_hi:[1,0]
	v_pk_add_f32 v[232:233], v[232:233], v[226:227] op_sel_hi:[1,0]
	v_pk_add_f32 v[234:235], v[234:235], v[226:227] op_sel_hi:[1,0]
	v_pk_add_f32 v[236:237], v[236:237], v[226:227] op_sel_hi:[1,0]
	v_rcp_f32_e32 v230, v230
	v_rcp_f32_e32 v231, v231
	v_rcp_f32_e32 v232, v232
	v_rcp_f32_e32 v233, v233
	v_rcp_f32_e32 v234, v234
	v_rcp_f32_e32 v235, v235
	v_rcp_f32_e32 v236, v236
	v_rcp_f32_e32 v237, v237
	v_pk_mul_f32 v[100:101], v[100:101], v[230:231]
	v_pk_mul_f32 v[102:103], v[102:103], v[232:233]
	v_pk_mul_f32 v[96:97], v[96:97], v[234:235]
	v_pk_mul_f32 v[98:99], v[98:99], v[236:237]
	v_pk_mul_f32 v[100:101], v[108:109], v[100:101]
	v_pk_mul_f32 v[102:103], v[110:111], v[102:103]
	v_pk_mul_f32 v[96:97], v[104:105], v[96:97]
	v_pk_mul_f32 v[98:99], v[106:107], v[98:99]
	v_cvt_pk_bf16_f32 v108, v100, v101
	v_cvt_pk_bf16_f32 v109, v102, v103
	v_cvt_pk_bf16_f32 v110, v96, v97
	v_cvt_pk_bf16_f32 v111, v98, v99
	global_store_dwordx4 v239, v[108:111], s[40:41]
	s_waitcnt vmcnt(12)
; __device__ __forceinline__ u32x4v pack8(const f32x4& a, const f32x4& b) { u32x4v w; w.x = cvt_pk_bf16(a[0], a[1]); w.y = cvt_pk_bf16(a[2], a[3]); w.z = cvt_pk_bf16(b[0], b[1]); w.w = cvt_pk_bf16(b[2], b[3]); return w; }
;     __device__ __forceinline__ void operator()(const f32x4 (&acc)[2][2][4][2], const Unit& u, int wr, int wc, int fr, int fq) const {
;     ...
;             for (int m = 0; m < 4; ++m) { const int r = row0 + ai * HALF + m * 16; const float rs = rstd_from_partials(part, r);
;                 f32x4 o[2];
; #pragma unroll
;                 for (int n = 0; n < 2; ++n) { const f32x4 g = acc[ai][0][m][n] * rs, up = acc[ai][1][m][n] * rs;
; #pragma unroll
;                     for (int e = 0; e < 4; ++e) o[n][e] = g[e] * __builtin_amdgcn_rcpf(1.0f + __builtin_amdgcn_exp2f(-1.44269504089f * g[e])) * up[e]; }
;                 *(u32x4v*)(H + (size_t)r * 2816 + hc0) = pack8(o[0], o[1]); }
	v_pk_add_f32 v[186:187], v[186:187], v[188:189]
	v_pk_add_f32 v[190:191], v[190:191], v[192:193]
	v_pk_add_f32 v[194:195], v[194:195], v[196:197]
	v_pk_add_f32 v[198:199], v[198:199], v[200:201]
	v_pk_add_f32 v[186:187], v[186:187], v[190:191]
	v_pk_add_f32 v[194:195], v[194:195], v[198:199]
	v_pk_add_f32 v[186:187], v[186:187], v[194:195]
	v_add_f32_e32 v186, v186, v187
	v_fmamk_f32 v222, v186, 0x3a800000, v152
	v_rsq_f32_e32 v222, v222
	global_load_dwordx4 v[186:189], v153, s[70:71] offset:2048
	global_load_dwordx4 v[190:193], v153, s[70:71] offset:2064
	global_load_dwordx4 v[194:197], v153, s[70:71] offset:2080
	global_load_dwordx4 v[198:201], v153, s[70:71] offset:2096
	v_add_u32_e32 v238, 0x2c000, v218
	v_pk_mul_f32 v[84:85], v[84:85], v[222:223] op_sel_hi:[1,0]
	v_pk_mul_f32 v[86:87], v[86:87], v[222:223] op_sel_hi:[1,0]
	v_pk_mul_f32 v[80:81], v[80:81], v[222:223] op_sel_hi:[1,0]
	v_pk_mul_f32 v[82:83], v[82:83], v[222:223] op_sel_hi:[1,0]
	v_pk_mul_f32 v[92:93], v[92:93], v[222:223] op_sel_hi:[1,0]
	v_pk_mul_f32 v[94:95], v[94:95], v[222:223] op_sel_hi:[1,0]
	v_pk_mul_f32 v[88:89], v[88:89], v[222:223] op_sel_hi:[1,0]
	v_pk_mul_f32 v[90:91], v[90:91], v[222:223] op_sel_hi:[1,0]
	v_pk_mul_f32 v[230:231], v[84:85], v[224:225] op_sel_hi:[1,0]
	v_pk_mul_f32 v[232:233], v[86:87], v[224:225] op_sel_hi:[1,0]
	v_pk_mul_f32 v[234:235], v[80:81], v[224:225] op_sel_hi:[1,0]
	v_pk_mul_f32 v[236:237], v[82:83], v[224:225] op_sel_hi:[1,0]
	v_exp_f32_e32 v230, v230
	v_exp_f32_e32 v231, v231
	v_exp_f32_e32 v232, v232
	v_exp_f32_e32 v233, v233
	v_exp_f32_e32 v234, v234
	v_exp_f32_e32 v235, v235
	v_exp_f32_e32 v236, v236
	v_exp_f32_e32 v237, v237
	v_pk_add_f32 v[230:231], v[230:231], v[226:227] op_sel_hi:[1,0]
	v_pk_add_f32 v[232:233], v[232:233], v[226:227] op_sel_hi:[1,0]
	v_pk_add_f32 v[234:235], v[234:235], v[226:227] op_sel_hi:[1,0]
	v_pk_add_f32 v[236:237], v[236:237], v[226:227] op_sel_hi:[1,0]
	v_rcp_f32_e32 v230, v230
	v_rcp_f32_e32 v231, v231
	v_rcp_f32_e32 v232, v232
	v_rcp_f32_e32 v233, v233
	v_rcp_f32_e32 v234, v234
	v_rcp_f32_e32 v235, v235
	v_rcp_f32_e32 v236, v236
	v_rcp_f32_e32 v237, v237
	v_pk_mul_f32 v[84:85], v[84:85], v[230:231]
	v_pk_mul_f32 v[86:87], v[86:87], v[232:233]
	v_pk_mul_f32 v[80:81], v[80:81], v[234:235]
	v_pk_mul_f32 v[82:83], v[82:83], v[236:237]
	v_pk_mul_f32 v[84:85], v[92:93], v[84:85]
	v_pk_mul_f32 v[86:87], v[94:95], v[86:87]
	v_pk_mul_f32 v[80:81], v[88:89], v[80:81]
	v_pk_mul_f32 v[82:83], v[90:91], v[82:83]
	v_cvt_pk_bf16_f32 v92, v84, v85
	v_cvt_pk_bf16_f32 v93, v86, v87
	v_cvt_pk_bf16_f32 v94, v80, v81
	v_cvt_pk_bf16_f32 v95, v82, v83
	global_store_dwordx4 v238, v[92:95], s[40:41]
	s_waitcnt vmcnt(12)
	v_pk_add_f32 v[202:203], v[202:203], v[204:205]
	v_pk_add_f32 v[206:207], v[206:207], v[208:209]
	v_pk_add_f32 v[210:211], v[210:211], v[212:213]
	v_pk_add_f32 v[214:215], v[214:215], v[216:217]
	v_pk_add_f32 v[202:203], v[202:203], v[206:207]
	v_pk_add_f32 v[210:211], v[210:211], v[214:215]
	v_pk_add_f32 v[202:203], v[202:203], v[210:211]
	v_add_f32_e32 v202, v202, v203
	v_fmamk_f32 v222, v202, 0x3a800000, v152
	v_rsq_f32_e32 v222, v222
	global_load_dwordx4 v[202:205], v153, s[70:71] offset:3072
	global_load_dwordx4 v[206:209], v153, s[70:71] offset:3088
	global_load_dwordx4 v[210:213], v153, s[70:71] offset:3104
	global_load_dwordx4 v[214:217], v153, s[70:71] offset:3120
	v_add_u32_e32 v239, 0x42000, v218
	v_pk_mul_f32 v[68:69], v[68:69], v[222:223] op_sel_hi:[1,0]
	v_pk_mul_f32 v[70:71], v[70:71], v[222:223] op_sel_hi:[1,0]
	v_pk_mul_f32 v[64:65], v[64:65], v[222:223] op_sel_hi:[1,0]
	v_pk_mul_f32 v[66:67], v[66:67], v[222:223] op_sel_hi:[1,0]
	v_pk_mul_f32 v[76:77], v[76:77], v[222:223] op_sel_hi:[1,0]
	v_pk_mul_f32 v[78:79], v[78:79], v[222:223] op_sel_hi:[1,0]
	v_pk_mul_f32 v[72:73], v[72:73], v[222:223] op_sel_hi:[1,0]
	v_pk_mul_f32 v[74:75], v[74:75], v[222:223] op_sel_hi:[1,0]
	v_pk_mul_f32 v[230:231], v[68:69], v[224:225] op_sel_hi:[1,0]
	v_pk_mul_f32 v[232:233], v[70:71], v[224:225] op_sel_hi:[1,0]
	v_pk_mul_f32 v[234:235], v[64:65], v[224:225] op_sel_hi:[1,0]
	v_pk_mul_f32 v[236:237], v[66:67], v[224:225] op_sel_hi:[1,0]
	v_exp_f32_e32 v230, v230
	v_exp_f32_e32 v231, v231
	v_exp_f32_e32 v232, v232
	v_exp_f32_e32 v233, v233
	v_exp_f32_e32 v234, v234
	v_exp_f32_e32 v235, v235
	v_exp_f32_e32 v236, v236
	v_exp_f32_e32 v237, v237
	v_pk_add_f32 v[230:231], v[230:231], v[226:227] op_sel_hi:[1,0]
	v_pk_add_f32 v[232:233], v[232:233], v[226:227] op_sel_hi:[1,0]
	v_pk_add_f32 v[234:235], v[234:235], v[226:227] op_sel_hi:[1,0]
	v_pk_add_f32 v[236:237], v[236:237], v[226:227] op_sel_hi:[1,0]
	v_rcp_f32_e32 v230, v230
	v_rcp_f32_e32 v231, v231
	v_rcp_f32_e32 v232, v232
	v_rcp_f32_e32 v233, v233
	v_rcp_f32_e32 v234, v234
	v_rcp_f32_e32 v235, v235
	v_rcp_f32_e32 v236, v236
	v_rcp_f32_e32 v237, v237
	v_pk_mul_f32 v[68:69], v[68:69], v[230:231]
	v_pk_mul_f32 v[70:71], v[70:71], v[232:233]
	v_pk_mul_f32 v[64:65], v[64:65], v[234:235]
	v_pk_mul_f32 v[66:67], v[66:67], v[236:237]
	v_pk_mul_f32 v[68:69], v[76:77], v[68:69]
	v_pk_mul_f32 v[70:71], v[78:79], v[70:71]
	v_pk_mul_f32 v[64:65], v[72:73], v[64:65]
	v_pk_mul_f32 v[66:67], v[74:75], v[66:67]
	v_cvt_pk_bf16_f32 v76, v68, v69
	v_cvt_pk_bf16_f32 v77, v70, v71
	v_cvt_pk_bf16_f32 v78, v64, v65
	v_cvt_pk_bf16_f32 v79, v66, v67
	global_store_dwordx4 v239, v[76:79], s[40:41]
	s_waitcnt vmcnt(12)
; __device__ __forceinline__ u32x4v pack8(const f32x4& a, const f32x4& b) { u32x4v w; w.x = cvt_pk_bf16(a[0], a[1]); w.y = cvt_pk_bf16(a[2], a[3]); w.z = cvt_pk_bf16(b[0], b[1]); w.w = cvt_pk_bf16(b[2], b[3]); return w; }
;     __device__ __forceinline__ void operator()(const f32x4 (&acc)[2][2][4][2], const Unit& u, int wr, int wc, int fr, int fq) const {
;     ...
;             for (int m = 0; m < 4; ++m) { const int r = row0 + ai * HALF + m * 16; const float rs = rstd_from_partials(part, r);
;                 f32x4 o[2];
; #pragma unroll
;                 for (int n = 0; n < 2; ++n) { const f32x4 g = acc[ai][0][m][n] * rs, up = acc[ai][1][m][n] * rs;
; #pragma unroll
;                     for (int e = 0; e < 4; ++e) o[n][e] = g[e] * __builtin_amdgcn_rcpf(1.0f + __builtin_amdgcn_exp2f(-1.44269504089f * g[e])) * up[e]; }
;                 *(u32x4v*)(H + (size_t)r * 2816 + hc0) = pack8(o[0], o[1]); }
	v_pk_add_f32 v[154:155], v[154:155], v[156:157]
	v_pk_add_f32 v[158:159], v[158:159], v[160:161]
	v_pk_add_f32 v[162:163], v[162:163], v[164:165]
	v_pk_add_f32 v[166:167], v[166:167], v[168:169]
	v_pk_add_f32 v[154:155], v[154:155], v[158:159]
	v_pk_add_f32 v[162:163], v[162:163], v[166:167]
	v_pk_add_f32 v[154:155], v[154:155], v[162:163]
	v_add_f32_e32 v154, v154, v155
	v_fmamk_f32 v222, v154, 0x3a800000, v152
	v_rsq_f32_e32 v222, v222
	s_nop 0
	v_add_u32_e32 v238, 0xb0000, v218
	v_pk_mul_f32 v[52:53], v[52:53], v[222:223] op_sel_hi:[1,0]
	v_pk_mul_f32 v[54:55], v[54:55], v[222:223] op_sel_hi:[1,0]
	v_pk_mul_f32 v[48:49], v[48:49], v[222:223] op_sel_hi:[1,0]
	v_pk_mul_f32 v[50:51], v[50:51], v[222:223] op_sel_hi:[1,0]
	v_pk_mul_f32 v[60:61], v[60:61], v[222:223] op_sel_hi:[1,0]
	v_pk_mul_f32 v[62:63], v[62:63], v[222:223] op_sel_hi:[1,0]
	v_pk_mul_f32 v[56:57], v[56:57], v[222:223] op_sel_hi:[1,0]
	v_pk_mul_f32 v[58:59], v[58:59], v[222:223] op_sel_hi:[1,0]
	v_pk_mul_f32 v[230:231], v[52:53], v[224:225] op_sel_hi:[1,0]
	v_pk_mul_f32 v[232:233], v[54:55], v[224:225] op_sel_hi:[1,0]
	v_pk_mul_f32 v[234:235], v[48:49], v[224:225] op_sel_hi:[1,0]
	v_pk_mul_f32 v[236:237], v[50:51], v[224:225] op_sel_hi:[1,0]
	v_exp_f32_e32 v230, v230
	v_exp_f32_e32 v231, v231
	v_exp_f32_e32 v232, v232
	v_exp_f32_e32 v233, v233
	v_exp_f32_e32 v234, v234
	v_exp_f32_e32 v235, v235
	v_exp_f32_e32 v236, v236
	v_exp_f32_e32 v237, v237
	v_pk_add_f32 v[230:231], v[230:231], v[226:227] op_sel_hi:[1,0]
	v_pk_add_f32 v[232:233], v[232:233], v[226:227] op_sel_hi:[1,0]
	v_pk_add_f32 v[234:235], v[234:235], v[226:227] op_sel_hi:[1,0]
	v_pk_add_f32 v[236:237], v[236:237], v[226:227] op_sel_hi:[1,0]
	v_rcp_f32_e32 v230, v230
	v_rcp_f32_e32 v231, v231
	v_rcp_f32_e32 v232, v232
	v_rcp_f32_e32 v233, v233
	v_rcp_f32_e32 v234, v234
	v_rcp_f32_e32 v235, v235
	v_rcp_f32_e32 v236, v236
	v_rcp_f32_e32 v237, v237
	v_pk_mul_f32 v[52:53], v[52:53], v[230:231]
	v_pk_mul_f32 v[54:55], v[54:55], v[232:233]
	v_pk_mul_f32 v[48:49], v[48:49], v[234:235]
	v_pk_mul_f32 v[50:51], v[50:51], v[236:237]
	v_pk_mul_f32 v[52:53], v[60:61], v[52:53]
	v_pk_mul_f32 v[54:55], v[62:63], v[54:55]
	v_pk_mul_f32 v[48:49], v[56:57], v[48:49]
	v_pk_mul_f32 v[50:51], v[58:59], v[50:51]
	v_cvt_pk_bf16_f32 v60, v52, v53
	v_cvt_pk_bf16_f32 v61, v54, v55
	v_cvt_pk_bf16_f32 v62, v48, v49
	v_cvt_pk_bf16_f32 v63, v50, v51
	global_store_dwordx4 v238, v[60:63], s[40:41]
	s_waitcnt vmcnt(8)
	v_pk_add_f32 v[170:171], v[170:171], v[172:173]
	v_pk_add_f32 v[174:175], v[174:175], v[176:177]
	v_pk_add_f32 v[178:179], v[178:179], v[180:181]
	v_pk_add_f32 v[182:183], v[182:183], v[184:185]
	v_pk_add_f32 v[170:171], v[170:171], v[174:175]
	v_pk_add_f32 v[178:179], v[178:179], v[182:183]
	v_pk_add_f32 v[170:171], v[170:171], v[178:179]
	v_add_f32_e32 v170, v170, v171
	v_fmamk_f32 v222, v170, 0x3a800000, v152
	v_rsq_f32_e32 v222, v222
	s_nop 0
	v_add_u32_e32 v239, 0xc6000, v218
	v_pk_mul_f32 v[36:37], v[36:37], v[222:223] op_sel_hi:[1,0]
	v_pk_mul_f32 v[38:39], v[38:39], v[222:223] op_sel_hi:[1,0]
	v_pk_mul_f32 v[32:33], v[32:33], v[222:223] op_sel_hi:[1,0]
	v_pk_mul_f32 v[34:35], v[34:35], v[222:223] op_sel_hi:[1,0]
	v_pk_mul_f32 v[44:45], v[44:45], v[222:223] op_sel_hi:[1,0]
	v_pk_mul_f32 v[46:47], v[46:47], v[222:223] op_sel_hi:[1,0]
	v_pk_mul_f32 v[40:41], v[40:41], v[222:223] op_sel_hi:[1,0]
	v_pk_mul_f32 v[42:43], v[42:43], v[222:223] op_sel_hi:[1,0]
	v_pk_mul_f32 v[230:231], v[36:37], v[224:225] op_sel_hi:[1,0]
	v_pk_mul_f32 v[232:233], v[38:39], v[224:225] op_sel_hi:[1,0]
	v_pk_mul_f32 v[234:235], v[32:33], v[224:225] op_sel_hi:[1,0]
	v_pk_mul_f32 v[236:237], v[34:35], v[224:225] op_sel_hi:[1,0]
	v_exp_f32_e32 v230, v230
	v_exp_f32_e32 v231, v231
	v_exp_f32_e32 v232, v232
	v_exp_f32_e32 v233, v233
	v_exp_f32_e32 v234, v234
	v_exp_f32_e32 v235, v235
	v_exp_f32_e32 v236, v236
	v_exp_f32_e32 v237, v237
	v_pk_add_f32 v[230:231], v[230:231], v[226:227] op_sel_hi:[1,0]
	v_pk_add_f32 v[232:233], v[232:233], v[226:227] op_sel_hi:[1,0]
	v_pk_add_f32 v[234:235], v[234:235], v[226:227] op_sel_hi:[1,0]
	v_pk_add_f32 v[236:237], v[236:237], v[226:227] op_sel_hi:[1,0]
	v_rcp_f32_e32 v230, v230
	v_rcp_f32_e32 v231, v231
	v_rcp_f32_e32 v232, v232
	v_rcp_f32_e32 v233, v233
	v_rcp_f32_e32 v234, v234
	v_rcp_f32_e32 v235, v235
	v_rcp_f32_e32 v236, v236
	v_rcp_f32_e32 v237, v237
	v_pk_mul_f32 v[36:37], v[36:37], v[230:231]
	v_pk_mul_f32 v[38:39], v[38:39], v[232:233]
	v_pk_mul_f32 v[32:33], v[32:33], v[234:235]
	v_pk_mul_f32 v[34:35], v[34:35], v[236:237]
	v_pk_mul_f32 v[36:37], v[44:45], v[36:37]
	v_pk_mul_f32 v[38:39], v[46:47], v[38:39]
	v_pk_mul_f32 v[32:33], v[40:41], v[32:33]
	v_pk_mul_f32 v[34:35], v[42:43], v[34:35]
	v_cvt_pk_bf16_f32 v44, v36, v37
	v_cvt_pk_bf16_f32 v45, v38, v39
	v_cvt_pk_bf16_f32 v46, v32, v33
	v_cvt_pk_bf16_f32 v47, v34, v35
	global_store_dwordx4 v239, v[44:47], s[40:41]
	s_waitcnt vmcnt(4)
; __device__ __forceinline__ u32x4v pack8(const f32x4& a, const f32x4& b) { u32x4v w; w.x = cvt_pk_bf16(a[0], a[1]); w.y = cvt_pk_bf16(a[2], a[3]); w.z = cvt_pk_bf16(b[0], b[1]); w.w = cvt_pk_bf16(b[2], b[3]); return w; }
; __device__ __forceinline__ float rstd_from_partials(const float* part, int row) {
;     const f32x4* p = (const f32x4*)(part + (size_t)row * 16); const f32x4 a = p[0], b = p[1], c = p[2], d = p[3];
;     const float s = ((a[0] + a[1]) + (a[2] + a[3])) + ((b[0] + b[1]) + (b[2] + b[3])) + ((c[0] + c[1]) + (c[2] + c[3])) + ((d[0] + d[1]) + (d[2] + d[3]));
;     return __builtin_amdgcn_rsqf(s * (1.0f / 1024.0f) + 1e-6f);
;     __device__ __forceinline__ void operator()(const f32x4 (&acc)[2][2][4][2], const Unit& u, int wr, int wc, int fr, int fq) const {
;     ...
;             for (int m = 0; m < 4; ++m) { const int r = row0 + ai * HALF + m * 16; const float rs = rstd_from_partials(part, r);
;                 f32x4 o[2];
; #pragma unroll
;                 for (int n = 0; n < 2; ++n) { const f32x4 g = acc[ai][0][m][n] * rs, up = acc[ai][1][m][n] * rs;
; #pragma unroll
;                     for (int e = 0; e < 4; ++e) o[n][e] = g[e] * __builtin_amdgcn_rcpf(1.0f + __builtin_amdgcn_exp2f(-1.44269504089f * g[e])) * up[e]; }
;                 *(u32x4v*)(H + (size_t)r * 2816 + hc0) = pack8(o[0], o[1]); }
	v_pk_add_f32 v[186:187], v[186:187], v[188:189]
	v_pk_add_f32 v[190:191], v[190:191], v[192:193]
	v_pk_add_f32 v[194:195], v[194:195], v[196:197]
	v_pk_add_f32 v[198:199], v[198:199], v[200:201]
	v_pk_add_f32 v[186:187], v[186:187], v[190:191]
	v_pk_add_f32 v[194:195], v[194:195], v[198:199]
	v_pk_add_f32 v[186:187], v[186:187], v[194:195]
	v_add_f32_e32 v186, v186, v187
	v_fmamk_f32 v222, v186, 0x3a800000, v152
	v_rsq_f32_e32 v222, v222
	s_nop 0
	v_add_u32_e32 v238, 0xdc000, v218
	v_pk_mul_f32 v[20:21], v[20:21], v[222:223] op_sel_hi:[1,0]
	v_pk_mul_f32 v[22:23], v[22:23], v[222:223] op_sel_hi:[1,0]
	v_pk_mul_f32 v[16:17], v[16:17], v[222:223] op_sel_hi:[1,0]
	v_pk_mul_f32 v[18:19], v[18:19], v[222:223] op_sel_hi:[1,0]
	v_pk_mul_f32 v[28:29], v[28:29], v[222:223] op_sel_hi:[1,0]
	v_pk_mul_f32 v[30:31], v[30:31], v[222:223] op_sel_hi:[1,0]
	v_pk_mul_f32 v[24:25], v[24:25], v[222:223] op_sel_hi:[1,0]
	v_pk_mul_f32 v[26:27], v[26:27], v[222:223] op_sel_hi:[1,0]
	v_pk_mul_f32 v[230:231], v[20:21], v[224:225] op_sel_hi:[1,0]
	v_pk_mul_f32 v[232:233], v[22:23], v[224:225] op_sel_hi:[1,0]
	v_pk_mul_f32 v[234:235], v[16:17], v[224:225] op_sel_hi:[1,0]
	v_pk_mul_f32 v[236:237], v[18:19], v[224:225] op_sel_hi:[1,0]
	v_exp_f32_e32 v230, v230
	v_exp_f32_e32 v231, v231
	v_exp_f32_e32 v232, v232
	v_exp_f32_e32 v233, v233
	v_exp_f32_e32 v234, v234
	v_exp_f32_e32 v235, v235
	v_exp_f32_e32 v236, v236
	v_exp_f32_e32 v237, v237
	v_pk_add_f32 v[230:231], v[230:231], v[226:227] op_sel_hi:[1,0]
	v_pk_add_f32 v[232:233], v[232:233], v[226:227] op_sel_hi:[1,0]
	v_pk_add_f32 v[234:235], v[234:235], v[226:227] op_sel_hi:[1,0]
	v_pk_add_f32 v[236:237], v[236:237], v[226:227] op_sel_hi:[1,0]
	v_rcp_f32_e32 v230, v230
	v_rcp_f32_e32 v231, v231
	v_rcp_f32_e32 v232, v232
	v_rcp_f32_e32 v233, v233
	v_rcp_f32_e32 v234, v234
	v_rcp_f32_e32 v235, v235
	v_rcp_f32_e32 v236, v236
	v_rcp_f32_e32 v237, v237
	v_pk_mul_f32 v[20:21], v[20:21], v[230:231]
	v_pk_mul_f32 v[22:23], v[22:23], v[232:233]
	v_pk_mul_f32 v[16:17], v[16:17], v[234:235]
	v_pk_mul_f32 v[18:19], v[18:19], v[236:237]
	v_pk_mul_f32 v[20:21], v[28:29], v[20:21]
	v_pk_mul_f32 v[22:23], v[30:31], v[22:23]
	v_pk_mul_f32 v[16:17], v[24:25], v[16:17]
	v_pk_mul_f32 v[18:19], v[26:27], v[18:19]
	v_cvt_pk_bf16_f32 v28, v20, v21
	v_cvt_pk_bf16_f32 v29, v22, v23
	v_cvt_pk_bf16_f32 v30, v16, v17
	v_cvt_pk_bf16_f32 v31, v18, v19
	global_store_dwordx4 v238, v[28:31], s[40:41]
	s_waitcnt vmcnt(0)
	v_pk_add_f32 v[202:203], v[202:203], v[204:205]
	v_pk_add_f32 v[206:207], v[206:207], v[208:209]
	v_pk_add_f32 v[210:211], v[210:211], v[212:213]
	v_pk_add_f32 v[214:215], v[214:215], v[216:217]
	v_pk_add_f32 v[202:203], v[202:203], v[206:207]
	v_pk_add_f32 v[210:211], v[210:211], v[214:215]
	v_pk_add_f32 v[202:203], v[202:203], v[210:211]
	v_add_f32_e32 v202, v202, v203
	v_fmamk_f32 v222, v202, 0x3a800000, v152
	v_rsq_f32_e32 v222, v222
	s_nop 0
	v_add_u32_e32 v239, 0xf2000, v218
	v_pk_mul_f32 v[4:5], v[4:5], v[222:223] op_sel_hi:[1,0]
	v_pk_mul_f32 v[6:7], v[6:7], v[222:223] op_sel_hi:[1,0]
	v_pk_mul_f32 v[0:1], v[0:1], v[222:223] op_sel_hi:[1,0]
	v_pk_mul_f32 v[2:3], v[2:3], v[222:223] op_sel_hi:[1,0]
	v_pk_mul_f32 v[12:13], v[12:13], v[222:223] op_sel_hi:[1,0]
	v_pk_mul_f32 v[14:15], v[14:15], v[222:223] op_sel_hi:[1,0]
	v_pk_mul_f32 v[8:9], v[8:9], v[222:223] op_sel_hi:[1,0]
	v_pk_mul_f32 v[10:11], v[10:11], v[222:223] op_sel_hi:[1,0]
	v_pk_mul_f32 v[230:231], v[4:5], v[224:225] op_sel_hi:[1,0]
	v_pk_mul_f32 v[232:233], v[6:7], v[224:225] op_sel_hi:[1,0]
	v_pk_mul_f32 v[234:235], v[0:1], v[224:225] op_sel_hi:[1,0]
	v_pk_mul_f32 v[236:237], v[2:3], v[224:225] op_sel_hi:[1,0]
	v_exp_f32_e32 v230, v230
	v_exp_f32_e32 v231, v231
	v_exp_f32_e32 v232, v232
	v_exp_f32_e32 v233, v233
	v_exp_f32_e32 v234, v234
	v_exp_f32_e32 v235, v235
	v_exp_f32_e32 v236, v236
	v_exp_f32_e32 v237, v237
	v_pk_add_f32 v[230:231], v[230:231], v[226:227] op_sel_hi:[1,0]
	v_pk_add_f32 v[232:233], v[232:233], v[226:227] op_sel_hi:[1,0]
	v_pk_add_f32 v[234:235], v[234:235], v[226:227] op_sel_hi:[1,0]
	v_pk_add_f32 v[236:237], v[236:237], v[226:227] op_sel_hi:[1,0]
	v_rcp_f32_e32 v230, v230
	v_rcp_f32_e32 v231, v231
	v_rcp_f32_e32 v232, v232
	v_rcp_f32_e32 v233, v233
	v_rcp_f32_e32 v234, v234
	v_rcp_f32_e32 v235, v235
	v_rcp_f32_e32 v236, v236
	v_rcp_f32_e32 v237, v237
	v_pk_mul_f32 v[4:5], v[4:5], v[230:231]
	v_pk_mul_f32 v[6:7], v[6:7], v[232:233]
	v_pk_mul_f32 v[0:1], v[0:1], v[234:235]
	v_pk_mul_f32 v[2:3], v[2:3], v[236:237]
	v_pk_mul_f32 v[4:5], v[12:13], v[4:5]
	v_pk_mul_f32 v[6:7], v[14:15], v[6:7]
	v_pk_mul_f32 v[0:1], v[8:9], v[0:1]
	v_pk_mul_f32 v[2:3], v[10:11], v[2:3]
	v_cvt_pk_bf16_f32 v12, v4, v5
	v_cvt_pk_bf16_f32 v13, v6, v7
	v_cvt_pk_bf16_f32 v14, v0, v1
	v_cvt_pk_bf16_f32 v15, v2, v3
	global_store_dwordx4 v239, v[12:15], s[40:41]
	s_andn2_b64 vcc, exec, s[0:1]
	s_mov_b64 s[0:1], -1
	s_cbranch_vccnz .LBB0_571
	s_andn2_b64 vcc, exec, s[8:9]
	s_cbranch_vccnz .LBB0_570
	s_barrier
	s_branch .LBB0_570

; __device__ __forceinline__ u32x4v pack8(const f32x4& a, const f32x4& b) { u32x4v w; w.x = cvt_pk_bf16(a[0], a[1]); w.y = cvt_pk_bf16(a[2], a[3]); w.z = cvt_pk_bf16(b[0], b[1]); w.w = cvt_pk_bf16(b[2], b[3]); return w; }
; __device__ __forceinline__ float rstd_from_partials(const float* part, int row) {
;     const f32x4* p = (const f32x4*)(part + (size_t)row * 16); const f32x4 a = p[0], b = p[1], c = p[2], d = p[3];
;     const float s = ((a[0] + a[1]) + (a[2] + a[3])) + ((b[0] + b[1]) + (b[2] + b[3])) + ((c[0] + c[1]) + (c[2] + c[3])) + ((d[0] + d[1]) + (d[2] + d[3]));
;     return __builtin_amdgcn_rsqf(s * (1.0f / 1024.0f) + 1e-6f);
;     __device__ __forceinline__ void operator()(const f32x4 (&acc)[2][2][4][2], const Unit& u, int wr, int wc, int fr, int fq) const {
;         const int row0 = u.pm * BM + wr * 64 + fr, hc0 = u.pn * HALF + wc * 32 + 8 * fq;
; #pragma unroll
;         for (int ai = 0; ai < 2; ++ai)
; #pragma unroll
;             for (int m = 0; m < 4; ++m) { const int r = row0 + ai * HALF + m * 16; const float rs = rstd_from_partials(part, r);
;                 f32x4 o[2];
; #pragma unroll
;                 for (int n = 0; n < 2; ++n) { const f32x4 g = acc[ai][0][m][n] * rs, up = acc[ai][1][m][n] * rs;
; #pragma unroll
;                     for (int e = 0; e < 4; ++e) o[n][e] = g[e] * __builtin_amdgcn_rcpf(1.0f + __builtin_amdgcn_exp2f(-1.44269504089f * g[e])) * up[e]; }
;                 *(u32x4v*)(H + (size_t)r * 2816 + hc0) = pack8(o[0], o[1]); }
.LBB0_1085:
	v_lshl_add_u32 v144, s22, 8, v146
	v_lshlrev_b32_e32 v145, 6, v144
	v_add_u32_e32 v153, 0x2000, v145
	global_load_dwordx4 v[154:157], v145, s[70:71] offset:0
	global_load_dwordx4 v[158:161], v145, s[70:71] offset:16
	global_load_dwordx4 v[162:165], v145, s[70:71] offset:32
	global_load_dwordx4 v[166:169], v145, s[70:71] offset:48
	global_load_dwordx4 v[170:173], v145, s[70:71] offset:1024
	global_load_dwordx4 v[174:177], v145, s[70:71] offset:1040
	global_load_dwordx4 v[178:181], v145, s[70:71] offset:1056
	global_load_dwordx4 v[182:185], v145, s[70:71] offset:1072
	global_load_dwordx4 v[186:189], v145, s[70:71] offset:2048
	global_load_dwordx4 v[190:193], v145, s[70:71] offset:2064
	global_load_dwordx4 v[194:197], v145, s[70:71] offset:2080
	global_load_dwordx4 v[198:201], v145, s[70:71] offset:2096
	global_load_dwordx4 v[202:205], v145, s[70:71] offset:3072
	global_load_dwordx4 v[206:209], v145, s[70:71] offset:3088
	global_load_dwordx4 v[210:213], v145, s[70:71] offset:3104
	global_load_dwordx4 v[214:217], v145, s[70:71] offset:3120
	v_mov_b32_e32 v224, 0xbfb8aa3b
	v_mov_b32_e32 v226, 1.0
	v_mul_u32_u24_e32 v218, s49, v144
	v_lshl_or_b32 v219, s50, 7, v148
	v_lshl_add_u32 v218, v219, 1, v218
	s_waitcnt vmcnt(12)
	v_pk_add_f32 v[154:155], v[154:155], v[156:157]
	v_pk_add_f32 v[158:159], v[158:159], v[160:161]
	v_pk_add_f32 v[162:163], v[162:163], v[164:165]
	v_pk_add_f32 v[166:167], v[166:167], v[168:169]
	v_pk_add_f32 v[154:155], v[154:155], v[158:159]
	v_pk_add_f32 v[162:163], v[162:163], v[166:167]
	v_pk_add_f32 v[154:155], v[154:155], v[162:163]
	v_add_f32_e32 v154, v154, v155
	v_fmamk_f32 v222, v154, 0x3a800000, v152
	v_rsq_f32_e32 v222, v222
	global_load_dwordx4 v[154:157], v153, s[70:71] offset:0
	global_load_dwordx4 v[158:161], v153, s[70:71] offset:16
	global_load_dwordx4 v[162:165], v153, s[70:71] offset:32
	global_load_dwordx4 v[166:169], v153, s[70:71] offset:48
	v_mov_b32_e32 v238, v218
	v_pk_mul_f32 v[116:117], v[116:117], v[222:223] op_sel_hi:[1,0]
	v_pk_mul_f32 v[118:119], v[118:119], v[222:223] op_sel_hi:[1,0]
	v_pk_mul_f32 v[112:113], v[112:113], v[222:223] op_sel_hi:[1,0]
	v_pk_mul_f32 v[114:115], v[114:115], v[222:223] op_sel_hi:[1,0]
	v_pk_mul_f32 v[124:125], v[124:125], v[222:223] op_sel_hi:[1,0]
	v_pk_mul_f32 v[126:127], v[126:127], v[222:223] op_sel_hi:[1,0]
	v_pk_mul_f32 v[120:121], v[120:121], v[222:223] op_sel_hi:[1,0]
	v_pk_mul_f32 v[122:123], v[122:123], v[222:223] op_sel_hi:[1,0]
	v_pk_mul_f32 v[230:231], v[116:117], v[224:225] op_sel_hi:[1,0]
	v_pk_mul_f32 v[232:233], v[118:119], v[224:225] op_sel_hi:[1,0]
	v_pk_mul_f32 v[234:235], v[112:113], v[224:225] op_sel_hi:[1,0]
	v_pk_mul_f32 v[236:237], v[114:115], v[224:225] op_sel_hi:[1,0]
	v_exp_f32_e32 v230, v230
	v_exp_f32_e32 v231, v231
	v_exp_f32_e32 v232, v232
	v_exp_f32_e32 v233, v233
	v_exp_f32_e32 v234, v234
	v_exp_f32_e32 v235, v235
	v_exp_f32_e32 v236, v236
	v_exp_f32_e32 v237, v237
	v_pk_add_f32 v[230:231], v[230:231], v[226:227] op_sel_hi:[1,0]
	v_pk_add_f32 v[232:233], v[232:233], v[226:227] op_sel_hi:[1,0]
	v_pk_add_f32 v[234:235], v[234:235], v[226:227] op_sel_hi:[1,0]
	v_pk_add_f32 v[236:237], v[236:237], v[226:227] op_sel_hi:[1,0]
	v_rcp_f32_e32 v230, v230
	v_rcp_f32_e32 v231, v231
	v_rcp_f32_e32 v232, v232
	v_rcp_f32_e32 v233, v233
	v_rcp_f32_e32 v234, v234
	v_rcp_f32_e32 v235, v235
	v_rcp_f32_e32 v236, v236
	v_rcp_f32_e32 v237, v237
	v_pk_mul_f32 v[116:117], v[116:117], v[230:231]
	v_pk_mul_f32 v[118:119], v[118:119], v[232:233]
	v_pk_mul_f32 v[112:113], v[112:113], v[234:235]
	v_pk_mul_f32 v[114:115], v[114:115], v[236:237]
	v_pk_mul_f32 v[116:117], v[124:125], v[116:117]
	v_pk_mul_f32 v[118:119], v[126:127], v[118:119]
	v_pk_mul_f32 v[112:113], v[120:121], v[112:113]
	v_pk_mul_f32 v[114:115], v[122:123], v[114:115]
	v_cvt_pk_bf16_f32 v124, v116, v117
	v_cvt_pk_bf16_f32 v125, v118, v119
	v_cvt_pk_bf16_f32 v126, v112, v113
	v_cvt_pk_bf16_f32 v127, v114, v115
	global_store_dwordx4 v238, v[124:127], s[40:41]
	s_waitcnt vmcnt(12)
	v_pk_add_f32 v[170:171], v[170:171], v[172:173]
	v_pk_add_f32 v[174:175], v[174:175], v[176:177]
	v_pk_add_f32 v[178:179], v[178:179], v[180:181]
	v_pk_add_f32 v[182:183], v[182:183], v[184:185]
	v_pk_add_f32 v[170:171], v[170:171], v[174:175]
	v_pk_add_f32 v[178:179], v[178:179], v[182:183]
	v_pk_add_f32 v[170:171], v[170:171], v[178:179]
	v_add_f32_e32 v170, v170, v171
	v_fmamk_f32 v222, v170, 0x3a800000, v152
	v_rsq_f32_e32 v222, v222
	global_load_dwordx4 v[170:173], v153, s[70:71] offset:1024
	global_load_dwordx4 v[174:177], v153, s[70:71] offset:1040
	global_load_dwordx4 v[178:181], v153, s[70:71] offset:1056
	global_load_dwordx4 v[182:185], v153, s[70:71] offset:1072
	v_add_u32_e32 v239, 0x16000, v218
	v_pk_mul_f32 v[100:101], v[100:101], v[222:223] op_sel_hi:[1,0]
	v_pk_mul_f32 v[102:103], v[102:103], v[222:223] op_sel_hi:[1,0]
	v_pk_mul_f32 v[96:97], v[96:97], v[222:223] op_sel_hi:[1,0]
	v_pk_mul_f32 v[98:99], v[98:99], v[222:223] op_sel_hi:[1,0]
	v_pk_mul_f32 v[108:109], v[108:109], v[222:223] op_sel_hi:[1,0]
	v_pk_mul_f32 v[110:111], v[110:111], v[222:223] op_sel_hi:[1,0]
	v_pk_mul_f32 v[104:105], v[104:105], v[222:223] op_sel_hi:[1,0]
	v_pk_mul_f32 v[106:107], v[106:107], v[222:223] op_sel_hi:[1,0]
	v_pk_mul_f32 v[230:231], v[100:101], v[224:225] op_sel_hi:[1,0]
	v_pk_mul_f32 v[232:233], v[102:103], v[224:225] op_sel_hi:[1,0]
	v_pk_mul_f32 v[234:235], v[96:97], v[224:225] op_sel_hi:[1,0]
	v_pk_mul_f32 v[236:237], v[98:99], v[224:225] op_sel_hi:[1,0]
	v_exp_f32_e32 v230, v230
	v_exp_f32_e32 v231, v231
	v_exp_f32_e32 v232, v232
	v_exp_f32_e32 v233, v233
	v_exp_f32_e32 v234, v234
	v_exp_f32_e32 v235, v235
	v_exp_f32_e32 v236, v236
	v_exp_f32_e32 v237, v237
	v_pk_add_f32 v[230:231], v[230:231], v[226:227] op_sel_hi:[1,0]
	v_pk_add_f32 v[232:233], v[232:233], v[226:227] op_sel_hi:[1,0]
	v_pk_add_f32 v[234:235], v[234:235], v[226:227] op_sel_hi:[1,0]
	v_pk_add_f32 v[236:237], v[236:237], v[226:227] op_sel_hi:[1,0]
	v_rcp_f32_e32 v230, v230
	v_rcp_f32_e32 v231, v231
	v_rcp_f32_e32 v232, v232
	v_rcp_f32_e32 v233, v233
	v_rcp_f32_e32 v234, v234
	v_rcp_f32_e32 v235, v235
	v_rcp_f32_e32 v236, v236
	v_rcp_f32_e32 v237, v237
	v_pk_mul_f32 v[100:101], v[100:101], v[230:231]
	v_pk_mul_f32 v[102:103], v[102:103], v[232:233]
	v_pk_mul_f32 v[96:97], v[96:97], v[234:235]
	v_pk_mul_f32 v[98:99], v[98:99], v[236:237]
	v_pk_mul_f32 v[100:101], v[108:109], v[100:101]
	v_pk_mul_f32 v[102:103], v[110:111], v[102:103]
	v_pk_mul_f32 v[96:97], v[104:105], v[96:97]
	v_pk_mul_f32 v[98:99], v[106:107], v[98:99]
	v_cvt_pk_bf16_f32 v108, v100, v101
	v_cvt_pk_bf16_f32 v109, v102, v103
	v_cvt_pk_bf16_f32 v110, v96, v97
	v_cvt_pk_bf16_f32 v111, v98, v99
	global_store_dwordx4 v239, v[108:111], s[40:41]
	s_waitcnt vmcnt(12)
; __device__ __forceinline__ u32x4v pack8(const f32x4& a, const f32x4& b) { u32x4v w; w.x = cvt_pk_bf16(a[0], a[1]); w.y = cvt_pk_bf16(a[2], a[3]); w.z = cvt_pk_bf16(b[0], b[1]); w.w = cvt_pk_bf16(b[2], b[3]); return w; }
; __device__ __forceinline__ float rstd_from_partials(const float* part, int row) {
;     const f32x4* p = (const f32x4*)(part + (size_t)row * 16); const f32x4 a = p[0], b = p[1], c = p[2], d = p[3];
;     const float s = ((a[0] + a[1]) + (a[2] + a[3])) + ((b[0] + b[1]) + (b[2] + b[3])) + ((c[0] + c[1]) + (c[2] + c[3])) + ((d[0] + d[1]) + (d[2] + d[3]));
;     return __builtin_amdgcn_rsqf(s * (1.0f / 1024.0f) + 1e-6f);
;     __device__ __forceinline__ void operator()(const f32x4 (&acc)[2][2][4][2], const Unit& u, int wr, int wc, int fr, int fq) const {
;     ...
;             for (int m = 0; m < 4; ++m) { const int r = row0 + ai * HALF + m * 16; const float rs = rstd_from_partials(part, r);
;                 f32x4 o[2];
; #pragma unroll
;                 for (int n = 0; n < 2; ++n) { const f32x4 g = acc[ai][0][m][n] * rs, up = acc[ai][1][m][n] * rs;
; #pragma unroll
;                     for (int e = 0; e < 4; ++e) o[n][e] = g[e] * __builtin_amdgcn_rcpf(1.0f + __builtin_amdgcn_exp2f(-1.44269504089f * g[e])) * up[e]; }
;                 *(u32x4v*)(H + (size_t)r * 2816 + hc0) = pack8(o[0], o[1]); }
	v_pk_add_f32 v[186:187], v[186:187], v[188:189]
	v_pk_add_f32 v[190:191], v[190:191], v[192:193]
	v_pk_add_f32 v[194:195], v[194:195], v[196:197]
	v_pk_add_f32 v[198:199], v[198:199], v[200:201]
	v_pk_add_f32 v[186:187], v[186:187], v[190:191]
	v_pk_add_f32 v[194:195], v[194:195], v[198:199]
	v_pk_add_f32 v[186:187], v[186:187], v[194:195]
	v_add_f32_e32 v186, v186, v187
	v_fmamk_f32 v222, v186, 0x3a800000, v152
	v_rsq_f32_e32 v222, v222
	global_load_dwordx4 v[186:189], v153, s[70:71] offset:2048
	global_load_dwordx4 v[190:193], v153, s[70:71] offset:2064
	global_load_dwordx4 v[194:197], v153, s[70:71] offset:2080
	global_load_dwordx4 v[198:201], v153, s[70:71] offset:2096
	v_add_u32_e32 v238, 0x2c000, v218
	v_pk_mul_f32 v[84:85], v[84:85], v[222:223] op_sel_hi:[1,0]
	v_pk_mul_f32 v[86:87], v[86:87], v[222:223] op_sel_hi:[1,0]
	v_pk_mul_f32 v[80:81], v[80:81], v[222:223] op_sel_hi:[1,0]
	v_pk_mul_f32 v[82:83], v[82:83], v[222:223] op_sel_hi:[1,0]
	v_pk_mul_f32 v[92:93], v[92:93], v[222:223] op_sel_hi:[1,0]
	v_pk_mul_f32 v[94:95], v[94:95], v[222:223] op_sel_hi:[1,0]
	v_pk_mul_f32 v[88:89], v[88:89], v[222:223] op_sel_hi:[1,0]
	v_pk_mul_f32 v[90:91], v[90:91], v[222:223] op_sel_hi:[1,0]
	v_pk_mul_f32 v[230:231], v[84:85], v[224:225] op_sel_hi:[1,0]
	v_pk_mul_f32 v[232:233], v[86:87], v[224:225] op_sel_hi:[1,0]
	v_pk_mul_f32 v[234:235], v[80:81], v[224:225] op_sel_hi:[1,0]
	v_pk_mul_f32 v[236:237], v[82:83], v[224:225] op_sel_hi:[1,0]
	v_exp_f32_e32 v230, v230
	v_exp_f32_e32 v231, v231
	v_exp_f32_e32 v232, v232
	v_exp_f32_e32 v233, v233
	v_exp_f32_e32 v234, v234
	v_exp_f32_e32 v235, v235
	v_exp_f32_e32 v236, v236
	v_exp_f32_e32 v237, v237
	v_pk_add_f32 v[230:231], v[230:231], v[226:227] op_sel_hi:[1,0]
	v_pk_add_f32 v[232:233], v[232:233], v[226:227] op_sel_hi:[1,0]
	v_pk_add_f32 v[234:235], v[234:235], v[226:227] op_sel_hi:[1,0]
	v_pk_add_f32 v[236:237], v[236:237], v[226:227] op_sel_hi:[1,0]
	v_rcp_f32_e32 v230, v230
	v_rcp_f32_e32 v231, v231
	v_rcp_f32_e32 v232, v232
	v_rcp_f32_e32 v233, v233
	v_rcp_f32_e32 v234, v234
	v_rcp_f32_e32 v235, v235
	v_rcp_f32_e32 v236, v236
	v_rcp_f32_e32 v237, v237
	v_pk_mul_f32 v[84:85], v[84:85], v[230:231]
	v_pk_mul_f32 v[86:87], v[86:87], v[232:233]
	v_pk_mul_f32 v[80:81], v[80:81], v[234:235]
	v_pk_mul_f32 v[82:83], v[82:83], v[236:237]
	v_pk_mul_f32 v[84:85], v[92:93], v[84:85]
	v_pk_mul_f32 v[86:87], v[94:95], v[86:87]
	v_pk_mul_f32 v[80:81], v[88:89], v[80:81]
	v_pk_mul_f32 v[82:83], v[90:91], v[82:83]
	v_cvt_pk_bf16_f32 v92, v84, v85
	v_cvt_pk_bf16_f32 v93, v86, v87
	v_cvt_pk_bf16_f32 v94, v80, v81
	v_cvt_pk_bf16_f32 v95, v82, v83
	global_store_dwordx4 v238, v[92:95], s[40:41]
	s_waitcnt vmcnt(12)
	v_pk_add_f32 v[202:203], v[202:203], v[204:205]
	v_pk_add_f32 v[206:207], v[206:207], v[208:209]
	v_pk_add_f32 v[210:211], v[210:211], v[212:213]
	v_pk_add_f32 v[214:215], v[214:215], v[216:217]
	v_pk_add_f32 v[202:203], v[202:203], v[206:207]
	v_pk_add_f32 v[210:211], v[210:211], v[214:215]
	v_pk_add_f32 v[202:203], v[202:203], v[210:211]
	v_add_f32_e32 v202, v202, v203
	v_fmamk_f32 v222, v202, 0x3a800000, v152
	v_rsq_f32_e32 v222, v222
	global_load_dwordx4 v[202:205], v153, s[70:71] offset:3072
	global_load_dwordx4 v[206:209], v153, s[70:71] offset:3088
	global_load_dwordx4 v[210:213], v153, s[70:71] offset:3104
	global_load_dwordx4 v[214:217], v153, s[70:71] offset:3120
	v_add_u32_e32 v239, 0x42000, v218
	v_pk_mul_f32 v[68:69], v[68:69], v[222:223] op_sel_hi:[1,0]
	v_pk_mul_f32 v[70:71], v[70:71], v[222:223] op_sel_hi:[1,0]
	v_pk_mul_f32 v[64:65], v[64:65], v[222:223] op_sel_hi:[1,0]
	v_pk_mul_f32 v[66:67], v[66:67], v[222:223] op_sel_hi:[1,0]
	v_pk_mul_f32 v[76:77], v[76:77], v[222:223] op_sel_hi:[1,0]
	v_pk_mul_f32 v[78:79], v[78:79], v[222:223] op_sel_hi:[1,0]
	v_pk_mul_f32 v[72:73], v[72:73], v[222:223] op_sel_hi:[1,0]
	v_pk_mul_f32 v[74:75], v[74:75], v[222:223] op_sel_hi:[1,0]
	v_pk_mul_f32 v[230:231], v[68:69], v[224:225] op_sel_hi:[1,0]
	v_pk_mul_f32 v[232:233], v[70:71], v[224:225] op_sel_hi:[1,0]
	v_pk_mul_f32 v[234:235], v[64:65], v[224:225] op_sel_hi:[1,0]
	v_pk_mul_f32 v[236:237], v[66:67], v[224:225] op_sel_hi:[1,0]
	v_exp_f32_e32 v230, v230
	v_exp_f32_e32 v231, v231
	v_exp_f32_e32 v232, v232
	v_exp_f32_e32 v233, v233
	v_exp_f32_e32 v234, v234
	v_exp_f32_e32 v235, v235
	v_exp_f32_e32 v236, v236
	v_exp_f32_e32 v237, v237
	v_pk_add_f32 v[230:231], v[230:231], v[226:227] op_sel_hi:[1,0]
	v_pk_add_f32 v[232:233], v[232:233], v[226:227] op_sel_hi:[1,0]
	v_pk_add_f32 v[234:235], v[234:235], v[226:227] op_sel_hi:[1,0]
	v_pk_add_f32 v[236:237], v[236:237], v[226:227] op_sel_hi:[1,0]
	v_rcp_f32_e32 v230, v230
	v_rcp_f32_e32 v231, v231
	v_rcp_f32_e32 v232, v232
	v_rcp_f32_e32 v233, v233
	v_rcp_f32_e32 v234, v234
	v_rcp_f32_e32 v235, v235
	v_rcp_f32_e32 v236, v236
	v_rcp_f32_e32 v237, v237
	v_pk_mul_f32 v[68:69], v[68:69], v[230:231]
	v_pk_mul_f32 v[70:71], v[70:71], v[232:233]
	v_pk_mul_f32 v[64:65], v[64:65], v[234:235]
	v_pk_mul_f32 v[66:67], v[66:67], v[236:237]
	v_pk_mul_f32 v[68:69], v[76:77], v[68:69]
	v_pk_mul_f32 v[70:71], v[78:79], v[70:71]
	v_pk_mul_f32 v[64:65], v[72:73], v[64:65]
	v_pk_mul_f32 v[66:67], v[74:75], v[66:67]
	v_cvt_pk_bf16_f32 v76, v68, v69
	v_cvt_pk_bf16_f32 v77, v70, v71
	v_cvt_pk_bf16_f32 v78, v64, v65
	v_cvt_pk_bf16_f32 v79, v66, v67
	global_store_dwordx4 v239, v[76:79], s[40:41]
	s_waitcnt vmcnt(12)
; __device__ __forceinline__ u32x4v pack8(const f32x4& a, const f32x4& b) { u32x4v w; w.x = cvt_pk_bf16(a[0], a[1]); w.y = cvt_pk_bf16(a[2], a[3]); w.z = cvt_pk_bf16(b[0], b[1]); w.w = cvt_pk_bf16(b[2], b[3]); return w; }
; __device__ __forceinline__ float rstd_from_partials(const float* part, int row) {
;     const f32x4* p = (const f32x4*)(part + (size_t)row * 16); const f32x4 a = p[0], b = p[1], c = p[2], d = p[3];
;     const float s = ((a[0] + a[1]) + (a[2] + a[3])) + ((b[0] + b[1]) + (b[2] + b[3])) + ((c[0] + c[1]) + (c[2] + c[3])) + ((d[0] + d[1]) + (d[2] + d[3]));
;     return __builtin_amdgcn_rsqf(s * (1.0f / 1024.0f) + 1e-6f);
;     __device__ __forceinline__ void operator()(const f32x4 (&acc)[2][2][4][2], const Unit& u, int wr, int wc, int fr, int fq) const {
;     ...
;             for (int m = 0; m < 4; ++m) { const int r = row0 + ai * HALF + m * 16; const float rs = rstd_from_partials(part, r);
;                 f32x4 o[2];
; #pragma unroll
;                 for (int n = 0; n < 2; ++n) { const f32x4 g = acc[ai][0][m][n] * rs, up = acc[ai][1][m][n] * rs;
; #pragma unroll
;                     for (int e = 0; e < 4; ++e) o[n][e] = g[e] * __builtin_amdgcn_rcpf(1.0f + __builtin_amdgcn_exp2f(-1.44269504089f * g[e])) * up[e]; }
;                 *(u32x4v*)(H + (size_t)r * 2816 + hc0) = pack8(o[0], o[1]); }
	v_pk_add_f32 v[154:155], v[154:155], v[156:157]
	v_pk_add_f32 v[158:159], v[158:159], v[160:161]
	v_pk_add_f32 v[162:163], v[162:163], v[164:165]
	v_pk_add_f32 v[166:167], v[166:167], v[168:169]
	v_pk_add_f32 v[154:155], v[154:155], v[158:159]
	v_pk_add_f32 v[162:163], v[162:163], v[166:167]
	v_pk_add_f32 v[154:155], v[154:155], v[162:163]
	v_add_f32_e32 v154, v154, v155
	v_fmamk_f32 v222, v154, 0x3a800000, v152
	v_rsq_f32_e32 v222, v222
	s_nop 0
	v_add_u32_e32 v238, 0xb0000, v218
	v_pk_mul_f32 v[52:53], v[52:53], v[222:223] op_sel_hi:[1,0]
	v_pk_mul_f32 v[54:55], v[54:55], v[222:223] op_sel_hi:[1,0]
	v_pk_mul_f32 v[48:49], v[48:49], v[222:223] op_sel_hi:[1,0]
	v_pk_mul_f32 v[50:51], v[50:51], v[222:223] op_sel_hi:[1,0]
	v_pk_mul_f32 v[60:61], v[60:61], v[222:223] op_sel_hi:[1,0]
	v_pk_mul_f32 v[62:63], v[62:63], v[222:223] op_sel_hi:[1,0]
	v_pk_mul_f32 v[56:57], v[56:57], v[222:223] op_sel_hi:[1,0]
	v_pk_mul_f32 v[58:59], v[58:59], v[222:223] op_sel_hi:[1,0]
	v_pk_mul_f32 v[230:231], v[52:53], v[224:225] op_sel_hi:[1,0]
	v_pk_mul_f32 v[232:233], v[54:55], v[224:225] op_sel_hi:[1,0]
	v_pk_mul_f32 v[234:235], v[48:49], v[224:225] op_sel_hi:[1,0]
	v_pk_mul_f32 v[236:237], v[50:51], v[224:225] op_sel_hi:[1,0]
	v_exp_f32_e32 v230, v230
	v_exp_f32_e32 v231, v231
	v_exp_f32_e32 v232, v232
	v_exp_f32_e32 v233, v233
	v_exp_f32_e32 v234, v234
	v_exp_f32_e32 v235, v235
	v_exp_f32_e32 v236, v236
	v_exp_f32_e32 v237, v237
	v_pk_add_f32 v[230:231], v[230:231], v[226:227] op_sel_hi:[1,0]
	v_pk_add_f32 v[232:233], v[232:233], v[226:227] op_sel_hi:[1,0]
	v_pk_add_f32 v[234:235], v[234:235], v[226:227] op_sel_hi:[1,0]
	v_pk_add_f32 v[236:237], v[236:237], v[226:227] op_sel_hi:[1,0]
	v_rcp_f32_e32 v230, v230
	v_rcp_f32_e32 v231, v231
	v_rcp_f32_e32 v232, v232
	v_rcp_f32_e32 v233, v233
	v_rcp_f32_e32 v234, v234
	v_rcp_f32_e32 v235, v235
	v_rcp_f32_e32 v236, v236
	v_rcp_f32_e32 v237, v237
	v_pk_mul_f32 v[52:53], v[52:53], v[230:231]
	v_pk_mul_f32 v[54:55], v[54:55], v[232:233]
	v_pk_mul_f32 v[48:49], v[48:49], v[234:235]
	v_pk_mul_f32 v[50:51], v[50:51], v[236:237]
	v_pk_mul_f32 v[52:53], v[60:61], v[52:53]
	v_pk_mul_f32 v[54:55], v[62:63], v[54:55]
	v_pk_mul_f32 v[48:49], v[56:57], v[48:49]
	v_pk_mul_f32 v[50:51], v[58:59], v[50:51]
	v_cvt_pk_bf16_f32 v60, v52, v53
	v_cvt_pk_bf16_f32 v61, v54, v55
	v_cvt_pk_bf16_f32 v62, v48, v49
	v_cvt_pk_bf16_f32 v63, v50, v51
	global_store_dwordx4 v238, v[60:63], s[40:41]
	s_waitcnt vmcnt(8)
	v_pk_add_f32 v[170:171], v[170:171], v[172:173]
	v_pk_add_f32 v[174:175], v[174:175], v[176:177]
	v_pk_add_f32 v[178:179], v[178:179], v[180:181]
	v_pk_add_f32 v[182:183], v[182:183], v[184:185]
	v_pk_add_f32 v[170:171], v[170:171], v[174:175]
	v_pk_add_f32 v[178:179], v[178:179], v[182:183]
	v_pk_add_f32 v[170:171], v[170:171], v[178:179]
	v_add_f32_e32 v170, v170, v171
	v_fmamk_f32 v222, v170, 0x3a800000, v152
	v_rsq_f32_e32 v222, v222
	s_nop 0
	v_add_u32_e32 v239, 0xc6000, v218
	v_pk_mul_f32 v[36:37], v[36:37], v[222:223] op_sel_hi:[1,0]
	v_pk_mul_f32 v[38:39], v[38:39], v[222:223] op_sel_hi:[1,0]
	v_pk_mul_f32 v[32:33], v[32:33], v[222:223] op_sel_hi:[1,0]
	v_pk_mul_f32 v[34:35], v[34:35], v[222:223] op_sel_hi:[1,0]
	v_pk_mul_f32 v[44:45], v[44:45], v[222:223] op_sel_hi:[1,0]
	v_pk_mul_f32 v[46:47], v[46:47], v[222:223] op_sel_hi:[1,0]
	v_pk_mul_f32 v[40:41], v[40:41], v[222:223] op_sel_hi:[1,0]
	v_pk_mul_f32 v[42:43], v[42:43], v[222:223] op_sel_hi:[1,0]
	v_pk_mul_f32 v[230:231], v[36:37], v[224:225] op_sel_hi:[1,0]
	v_pk_mul_f32 v[232:233], v[38:39], v[224:225] op_sel_hi:[1,0]
	v_pk_mul_f32 v[234:235], v[32:33], v[224:225] op_sel_hi:[1,0]
	v_pk_mul_f32 v[236:237], v[34:35], v[224:225] op_sel_hi:[1,0]
	v_exp_f32_e32 v230, v230
	v_exp_f32_e32 v231, v231
	v_exp_f32_e32 v232, v232
	v_exp_f32_e32 v233, v233
	v_exp_f32_e32 v234, v234
	v_exp_f32_e32 v235, v235
	v_exp_f32_e32 v236, v236
	v_exp_f32_e32 v237, v237
	v_pk_add_f32 v[230:231], v[230:231], v[226:227] op_sel_hi:[1,0]
	v_pk_add_f32 v[232:233], v[232:233], v[226:227] op_sel_hi:[1,0]
	v_pk_add_f32 v[234:235], v[234:235], v[226:227] op_sel_hi:[1,0]
	v_pk_add_f32 v[236:237], v[236:237], v[226:227] op_sel_hi:[1,0]
	v_rcp_f32_e32 v230, v230
	v_rcp_f32_e32 v231, v231
	v_rcp_f32_e32 v232, v232
	v_rcp_f32_e32 v233, v233
	v_rcp_f32_e32 v234, v234
	v_rcp_f32_e32 v235, v235
	v_rcp_f32_e32 v236, v236
	v_rcp_f32_e32 v237, v237
	v_pk_mul_f32 v[36:37], v[36:37], v[230:231]
	v_pk_mul_f32 v[38:39], v[38:39], v[232:233]
	v_pk_mul_f32 v[32:33], v[32:33], v[234:235]
	v_pk_mul_f32 v[34:35], v[34:35], v[236:237]
	v_pk_mul_f32 v[36:37], v[44:45], v[36:37]
	v_pk_mul_f32 v[38:39], v[46:47], v[38:39]
	v_pk_mul_f32 v[32:33], v[40:41], v[32:33]
	v_pk_mul_f32 v[34:35], v[42:43], v[34:35]
	v_cvt_pk_bf16_f32 v44, v36, v37
	v_cvt_pk_bf16_f32 v45, v38, v39
	v_cvt_pk_bf16_f32 v46, v32, v33
	v_cvt_pk_bf16_f32 v47, v34, v35
	global_store_dwordx4 v239, v[44:47], s[40:41]
	s_waitcnt vmcnt(4)
; __device__ __forceinline__ u32x4v pack8(const f32x4& a, const f32x4& b) { u32x4v w; w.x = cvt_pk_bf16(a[0], a[1]); w.y = cvt_pk_bf16(a[2], a[3]); w.z = cvt_pk_bf16(b[0], b[1]); w.w = cvt_pk_bf16(b[2], b[3]); return w; }
; __device__ __forceinline__ float rstd_from_partials(const float* part, int row) {
;     const f32x4* p = (const f32x4*)(part + (size_t)row * 16); const f32x4 a = p[0], b = p[1], c = p[2], d = p[3];
;     const float s = ((a[0] + a[1]) + (a[2] + a[3])) + ((b[0] + b[1]) + (b[2] + b[3])) + ((c[0] + c[1]) + (c[2] + c[3])) + ((d[0] + d[1]) + (d[2] + d[3]));
;     return __builtin_amdgcn_rsqf(s * (1.0f / 1024.0f) + 1e-6f);
;     __device__ __forceinline__ void operator()(const f32x4 (&acc)[2][2][4][2], const Unit& u, int wr, int wc, int fr, int fq) const {
;     ...
;             for (int m = 0; m < 4; ++m) { const int r = row0 + ai * HALF + m * 16; const float rs = rstd_from_partials(part, r);
;                 f32x4 o[2];
; #pragma unroll
;                 for (int n = 0; n < 2; ++n) { const f32x4 g = acc[ai][0][m][n] * rs, up = acc[ai][1][m][n] * rs;
; #pragma unroll
;                     for (int e = 0; e < 4; ++e) o[n][e] = g[e] * __builtin_amdgcn_rcpf(1.0f + __builtin_amdgcn_exp2f(-1.44269504089f * g[e])) * up[e]; }
;                 *(u32x4v*)(H + (size_t)r * 2816 + hc0) = pack8(o[0], o[1]); }
	v_pk_add_f32 v[186:187], v[186:187], v[188:189]
	v_pk_add_f32 v[190:191], v[190:191], v[192:193]
	v_pk_add_f32 v[194:195], v[194:195], v[196:197]
	v_pk_add_f32 v[198:199], v[198:199], v[200:201]
	v_pk_add_f32 v[186:187], v[186:187], v[190:191]
	v_pk_add_f32 v[194:195], v[194:195], v[198:199]
	v_pk_add_f32 v[186:187], v[186:187], v[194:195]
	v_add_f32_e32 v186, v186, v187
	v_fmamk_f32 v222, v186, 0x3a800000, v152
	v_rsq_f32_e32 v222, v222
	s_nop 0
	v_add_u32_e32 v238, 0xdc000, v218
	v_pk_mul_f32 v[20:21], v[20:21], v[222:223] op_sel_hi:[1,0]
	v_pk_mul_f32 v[22:23], v[22:23], v[222:223] op_sel_hi:[1,0]
	v_pk_mul_f32 v[16:17], v[16:17], v[222:223] op_sel_hi:[1,0]
	v_pk_mul_f32 v[18:19], v[18:19], v[222:223] op_sel_hi:[1,0]
	v_pk_mul_f32 v[28:29], v[28:29], v[222:223] op_sel_hi:[1,0]
	v_pk_mul_f32 v[30:31], v[30:31], v[222:223] op_sel_hi:[1,0]
	v_pk_mul_f32 v[24:25], v[24:25], v[222:223] op_sel_hi:[1,0]
	v_pk_mul_f32 v[26:27], v[26:27], v[222:223] op_sel_hi:[1,0]
	v_pk_mul_f32 v[230:231], v[20:21], v[224:225] op_sel_hi:[1,0]
	v_pk_mul_f32 v[232:233], v[22:23], v[224:225] op_sel_hi:[1,0]
	v_pk_mul_f32 v[234:235], v[16:17], v[224:225] op_sel_hi:[1,0]
	v_pk_mul_f32 v[236:237], v[18:19], v[224:225] op_sel_hi:[1,0]
	v_exp_f32_e32 v230, v230
	v_exp_f32_e32 v231, v231
	v_exp_f32_e32 v232, v232
	v_exp_f32_e32 v233, v233
	v_exp_f32_e32 v234, v234
	v_exp_f32_e32 v235, v235
	v_exp_f32_e32 v236, v236
	v_exp_f32_e32 v237, v237
	v_pk_add_f32 v[230:231], v[230:231], v[226:227] op_sel_hi:[1,0]
	v_pk_add_f32 v[232:233], v[232:233], v[226:227] op_sel_hi:[1,0]
	v_pk_add_f32 v[234:235], v[234:235], v[226:227] op_sel_hi:[1,0]
	v_pk_add_f32 v[236:237], v[236:237], v[226:227] op_sel_hi:[1,0]
	v_rcp_f32_e32 v230, v230
	v_rcp_f32_e32 v231, v231
	v_rcp_f32_e32 v232, v232
	v_rcp_f32_e32 v233, v233
	v_rcp_f32_e32 v234, v234
	v_rcp_f32_e32 v235, v235
	v_rcp_f32_e32 v236, v236
	v_rcp_f32_e32 v237, v237
	v_pk_mul_f32 v[20:21], v[20:21], v[230:231]
	v_pk_mul_f32 v[22:23], v[22:23], v[232:233]
	v_pk_mul_f32 v[16:17], v[16:17], v[234:235]
	v_pk_mul_f32 v[18:19], v[18:19], v[236:237]
	v_pk_mul_f32 v[20:21], v[28:29], v[20:21]
	v_pk_mul_f32 v[22:23], v[30:31], v[22:23]
	v_pk_mul_f32 v[16:17], v[24:25], v[16:17]
	v_pk_mul_f32 v[18:19], v[26:27], v[18:19]
	v_cvt_pk_bf16_f32 v28, v20, v21
	v_cvt_pk_bf16_f32 v29, v22, v23
	v_cvt_pk_bf16_f32 v30, v16, v17
	v_cvt_pk_bf16_f32 v31, v18, v19
	global_store_dwordx4 v238, v[28:31], s[40:41]
	s_waitcnt vmcnt(0)
	v_pk_add_f32 v[202:203], v[202:203], v[204:205]
	v_pk_add_f32 v[206:207], v[206:207], v[208:209]
	v_pk_add_f32 v[210:211], v[210:211], v[212:213]
	v_pk_add_f32 v[214:215], v[214:215], v[216:217]
	v_pk_add_f32 v[202:203], v[202:203], v[206:207]
	v_pk_add_f32 v[210:211], v[210:211], v[214:215]
	v_pk_add_f32 v[202:203], v[202:203], v[210:211]
	v_add_f32_e32 v202, v202, v203
	v_fmamk_f32 v222, v202, 0x3a800000, v152
	v_rsq_f32_e32 v222, v222
	s_nop 0
	v_add_u32_e32 v239, 0xf2000, v218
	v_pk_mul_f32 v[4:5], v[4:5], v[222:223] op_sel_hi:[1,0]
	v_pk_mul_f32 v[6:7], v[6:7], v[222:223] op_sel_hi:[1,0]
	v_pk_mul_f32 v[0:1], v[0:1], v[222:223] op_sel_hi:[1,0]
	v_pk_mul_f32 v[2:3], v[2:3], v[222:223] op_sel_hi:[1,0]
	v_pk_mul_f32 v[12:13], v[12:13], v[222:223] op_sel_hi:[1,0]
	v_pk_mul_f32 v[14:15], v[14:15], v[222:223] op_sel_hi:[1,0]
	v_pk_mul_f32 v[8:9], v[8:9], v[222:223] op_sel_hi:[1,0]
	v_pk_mul_f32 v[10:11], v[10:11], v[222:223] op_sel_hi:[1,0]
	v_pk_mul_f32 v[230:231], v[4:5], v[224:225] op_sel_hi:[1,0]
	v_pk_mul_f32 v[232:233], v[6:7], v[224:225] op_sel_hi:[1,0]
	v_pk_mul_f32 v[234:235], v[0:1], v[224:225] op_sel_hi:[1,0]
	v_pk_mul_f32 v[236:237], v[2:3], v[224:225] op_sel_hi:[1,0]
	v_exp_f32_e32 v230, v230
	v_exp_f32_e32 v231, v231
	v_exp_f32_e32 v232, v232
	v_exp_f32_e32 v233, v233
	v_exp_f32_e32 v234, v234
	v_exp_f32_e32 v235, v235
	v_exp_f32_e32 v236, v236
	v_exp_f32_e32 v237, v237
	v_pk_add_f32 v[230:231], v[230:231], v[226:227] op_sel_hi:[1,0]
	v_pk_add_f32 v[232:233], v[232:233], v[226:227] op_sel_hi:[1,0]
	v_pk_add_f32 v[234:235], v[234:235], v[226:227] op_sel_hi:[1,0]
	v_pk_add_f32 v[236:237], v[236:237], v[226:227] op_sel_hi:[1,0]
	v_rcp_f32_e32 v230, v230
	v_rcp_f32_e32 v231, v231
	v_rcp_f32_e32 v232, v232
	v_rcp_f32_e32 v233, v233
	v_rcp_f32_e32 v234, v234
	v_rcp_f32_e32 v235, v235
	v_rcp_f32_e32 v236, v236
	v_rcp_f32_e32 v237, v237
	v_pk_mul_f32 v[4:5], v[4:5], v[230:231]
	v_pk_mul_f32 v[6:7], v[6:7], v[232:233]
	v_pk_mul_f32 v[0:1], v[0:1], v[234:235]
	v_pk_mul_f32 v[2:3], v[2:3], v[236:237]
	v_pk_mul_f32 v[4:5], v[12:13], v[4:5]
	v_pk_mul_f32 v[6:7], v[14:15], v[6:7]
	v_pk_mul_f32 v[0:1], v[8:9], v[0:1]
	v_pk_mul_f32 v[2:3], v[10:11], v[2:3]
	v_cvt_pk_bf16_f32 v12, v4, v5
	v_cvt_pk_bf16_f32 v13, v6, v7
	v_cvt_pk_bf16_f32 v14, v0, v1
	v_cvt_pk_bf16_f32 v15, v2, v3
	global_store_dwordx4 v239, v[12:15], s[40:41]
	s_andn2_b64 vcc, exec, s[0:1]
	s_mov_b64 s[0:1], -1
	s_cbranch_vccnz .LBB0_1078
	s_andn2_b64 vcc, exec, s[8:9]
	s_cbranch_vccnz .LBB0_1077
	s_barrier
	s_branch .LBB0_1077
